# k14 + in-place bf16 residual epilogue (6 sites) rewritten: saddr 32-bit offsets, counted vmcnt per row group, packed f32 square sums, one permlane32/16-swap reduction + 2 stores instead of 16 ds_bperm
# speedup vs baseline: 1.0082x; 1.0082x over previous
; __device__ __forceinline__ unsigned cvtpk(float lo, float hi) { f32x2_t v = {lo, hi}; bf16x2_t b = __builtin_convertvector(v, bf16x2_t); return __builtin_bit_cast(unsigned, b); }
;     __device__ __forceinline__ void operator()(const f32x4 (&acc)[2][2][4][2], const Unit& u, int wr, int wc, int fr, int fq) const {
;         const int row0 = u.pm * BM + wr * 64 + fr, col0 = u.pn * BM + wc * 32 + 8 * fq;
;         u32x4 xv[RM == 0 ? 1 : 2][RM == 0 ? 1 : 4][RM == 0 ? 1 : 2];
;         if (RM != 0) {
; #pragma unroll
;             for (int ai = 0; ai < 2; ++ai)
; #pragma unroll
;                 for (int m = 0; m < 4; ++m)
; #pragma unroll
;                     for (int bj = 0; bj < 2; ++bj) xv[RM == 0 ? 0 : ai][RM == 0 ? 0 : m][RM == 0 ? 0 : bj] = *(const u32x4*)(xb + (size_t)(row0 + ai * HALF + m * 16) * DM + col0 + bj * HALF);
;         }
; #pragma unroll
;         for (int ai = 0; ai < 2; ++ai)
; #pragma unroll
;             for (int m = 0; m < 4; ++m) {
;                 const int row = row0 + ai * HALF + m * 16; float s = 0.f;
; #pragma unroll
;                 for (int bj = 0; bj < 2; ++bj) {
;                     const size_t off = (size_t)row * DM + col0 + bj * HALF;
;                     f32x4 v0, v1;
;                     if (RM == 0) { v0 = *(const f32x4*)(xf + off); v1 = *(const f32x4*)(xf + off + 4); }
;                     else { const u32x4 w = xv[RM == 0 ? 0 : ai][RM == 0 ? 0 : m][RM == 0 ? 0 : bj]; v0 = (f32x4){bflo(w.x), bfhi(w.x), bflo(w.y), bfhi(w.y)}; v1 = (f32x4){bflo(w.z), bfhi(w.z), bflo(w.w), bfhi(w.w)}; }
;                     v0 = v0 + acc[ai][bj][m][0] * alpha; v1 = v1 + acc[ai][bj][m][1] * alpha;
;                     if (RM == 2) { *(f32x4*)(outf + off) = v0; *(f32x4*)(outf + off + 4) = v1; }
;                     else {
;                         u32x4 w; w.x = cvtpk(v0[0], v0[1]); w.y = cvtpk(v0[2], v0[3]); w.z = cvtpk(v1[0], v1[1]); w.w = cvtpk(v1[2], v1[3]);
;                         *(u32x4*)(xb + off) = w;
;                         s += (v0[0] * v0[0] + v0[1] * v0[1]) + (v0[2] * v0[2] + v0[3] * v0[3]) + (v1[0] * v1[0] + v1[1] * v1[1]) + (v1[2] * v1[2] + v1[3] * v1[3]);
;                     }
;                 }
;                 if (RM != 2) { s += __shfl_xor(s, 16); s += __shfl_xor(s, 32); if (fq == 0) ssq_out[(size_t)row * 16 + u.pn * 4 + wc] = s; }
.LBB0_717:
	v_lshl_or_b32 v232, s12, 8, v242
	v_lshl_add_u32 v233, s34, 8, v240
	v_lshlrev_b32_e32 v204, 11, v233
	v_lshl_add_u32 v204, v232, 1, v204
	v_add_u32_e32 v205, 0x8000, v204
	v_add_u32_e32 v206, 0x10000, v204
	v_add_u32_e32 v207, 0x18000, v204
	v_add_u32_e32 v208, 0x40000, v204
	v_add_u32_e32 v209, 0x48000, v204
	v_add_u32_e32 v210, 0x50000, v204
	v_add_u32_e32 v211, 0x58000, v204
	global_load_dwordx4 v[152:155], v204, s[16:17]
	global_load_dwordx4 v[156:159], v204, s[16:17] offset:256
	global_load_dwordx4 v[160:163], v205, s[16:17]
	global_load_dwordx4 v[164:167], v205, s[16:17] offset:256
	global_load_dwordx4 v[168:171], v206, s[16:17]
	global_load_dwordx4 v[172:175], v206, s[16:17] offset:256
	global_load_dwordx4 v[176:179], v207, s[16:17]
	global_load_dwordx4 v[180:183], v207, s[16:17] offset:256
	global_load_dwordx4 v[184:187], v208, s[16:17]
	global_load_dwordx4 v[188:191], v208, s[16:17] offset:256
	global_load_dwordx4 v[120:123], v209, s[16:17]
	global_load_dwordx4 v[124:127], v209, s[16:17] offset:256
	global_load_dwordx4 v[128:131], v210, s[16:17]
	global_load_dwordx4 v[132:135], v210, s[16:17] offset:256
	global_load_dwordx4 v[136:139], v211, s[16:17]
	global_load_dwordx4 v[140:143], v211, s[16:17] offset:256
	v_mbcnt_lo_u32_b32 v234, -1, 0
	v_mbcnt_hi_u32_b32 v234, -1, v234
	v_lshrrev_b32_e32 v235, 4, v234
	v_and_b32_e32 v236, 1, v235
	v_lshlrev_b32_e32 v236, 5, v236
	v_lshrrev_b32_e32 v235, 1, v235
	v_lshl_add_u32 v236, v235, 4, v236
	v_add_u32_e32 v236, v233, v236
	v_lshlrev_b32_e32 v236, 6, v236
	s_lshl_b32 s36, s12, 4
	s_lshl_b32 s37, s44, 2
	s_add_u32 s36, s36, s37
	v_add_u32_e32 v236, s36, v236
	v_add_u32_e32 v237, 0x2000, v236
	s_waitcnt vmcnt(14)
	v_lshlrev_b32_e32 v222, 16, v152
	v_and_b32_e32 v223, 0xffff0000, v152
	v_lshlrev_b32_e32 v224, 16, v153
	v_and_b32_e32 v225, 0xffff0000, v153
	v_lshlrev_b32_e32 v226, 16, v154
	v_and_b32_e32 v227, 0xffff0000, v154
	v_lshlrev_b32_e32 v228, 16, v155
	v_and_b32_e32 v229, 0xffff0000, v155
	v_pk_add_f32 v[148:149], v[148:149], v[222:223]
	v_pk_add_f32 v[150:151], v[150:151], v[224:225]
	v_pk_add_f32 v[144:145], v[144:145], v[226:227]
	v_pk_add_f32 v[146:147], v[146:147], v[228:229]
	v_cvt_pk_bf16_f32 v152, v148, v149
	v_cvt_pk_bf16_f32 v153, v150, v151
	v_cvt_pk_bf16_f32 v154, v144, v145
	v_cvt_pk_bf16_f32 v155, v146, v147
	global_store_dwordx4 v204, v[152:155], s[16:17]
	v_pk_mul_f32 v[220:221], v[148:149], v[148:149]
	v_pk_fma_f32 v[220:221], v[150:151], v[150:151], v[220:221]
	v_pk_fma_f32 v[220:221], v[144:145], v[144:145], v[220:221]
	v_pk_fma_f32 v[220:221], v[146:147], v[146:147], v[220:221]
	v_lshlrev_b32_e32 v222, 16, v156
	v_and_b32_e32 v223, 0xffff0000, v156
	v_lshlrev_b32_e32 v224, 16, v157
	v_and_b32_e32 v225, 0xffff0000, v157
	v_lshlrev_b32_e32 v226, 16, v158
	v_and_b32_e32 v227, 0xffff0000, v158
	v_lshlrev_b32_e32 v228, 16, v159
	v_and_b32_e32 v229, 0xffff0000, v159
	v_pk_add_f32 v[116:117], v[116:117], v[222:223]
	v_pk_add_f32 v[118:119], v[118:119], v[224:225]
	v_pk_add_f32 v[112:113], v[112:113], v[226:227]
	v_pk_add_f32 v[114:115], v[114:115], v[228:229]
	v_cvt_pk_bf16_f32 v156, v116, v117
	v_cvt_pk_bf16_f32 v157, v118, v119
	v_cvt_pk_bf16_f32 v158, v112, v113
	v_cvt_pk_bf16_f32 v159, v114, v115
	global_store_dwordx4 v204, v[156:159], s[16:17] offset:256
	v_pk_mul_f32 v[230:231], v[116:117], v[116:117]
	v_pk_fma_f32 v[230:231], v[118:119], v[118:119], v[230:231]
	v_pk_fma_f32 v[230:231], v[112:113], v[112:113], v[230:231]
	v_pk_fma_f32 v[230:231], v[114:115], v[114:115], v[230:231]
	v_pk_add_f32 v[220:221], v[220:221], v[230:231]
	v_add_f32_e32 v212, v220, v221
	s_waitcnt vmcnt(14)
	v_lshlrev_b32_e32 v222, 16, v160
	v_and_b32_e32 v223, 0xffff0000, v160
	v_lshlrev_b32_e32 v224, 16, v161
	v_and_b32_e32 v225, 0xffff0000, v161
	v_lshlrev_b32_e32 v226, 16, v162
	v_and_b32_e32 v227, 0xffff0000, v162
	v_lshlrev_b32_e32 v228, 16, v163
	v_and_b32_e32 v229, 0xffff0000, v163
	v_pk_add_f32 v[108:109], v[108:109], v[222:223]
	v_pk_add_f32 v[110:111], v[110:111], v[224:225]
	v_pk_add_f32 v[104:105], v[104:105], v[226:227]
	v_pk_add_f32 v[106:107], v[106:107], v[228:229]
	v_cvt_pk_bf16_f32 v160, v108, v109
	v_cvt_pk_bf16_f32 v161, v110, v111
	v_cvt_pk_bf16_f32 v162, v104, v105
	v_cvt_pk_bf16_f32 v163, v106, v107
	global_store_dwordx4 v205, v[160:163], s[16:17]
	v_pk_mul_f32 v[220:221], v[108:109], v[108:109]
	v_pk_fma_f32 v[220:221], v[110:111], v[110:111], v[220:221]
	v_pk_fma_f32 v[220:221], v[104:105], v[104:105], v[220:221]
	v_pk_fma_f32 v[220:221], v[106:107], v[106:107], v[220:221]
	v_lshlrev_b32_e32 v222, 16, v164
	v_and_b32_e32 v223, 0xffff0000, v164
	v_lshlrev_b32_e32 v224, 16, v165
	v_and_b32_e32 v225, 0xffff0000, v165
	v_lshlrev_b32_e32 v226, 16, v166
	v_and_b32_e32 v227, 0xffff0000, v166
	v_lshlrev_b32_e32 v228, 16, v167
	v_and_b32_e32 v229, 0xffff0000, v167
	v_pk_add_f32 v[100:101], v[100:101], v[222:223]
	v_pk_add_f32 v[102:103], v[102:103], v[224:225]
	v_pk_add_f32 v[96:97], v[96:97], v[226:227]
	v_pk_add_f32 v[98:99], v[98:99], v[228:229]
	v_cvt_pk_bf16_f32 v164, v100, v101
	v_cvt_pk_bf16_f32 v165, v102, v103
	v_cvt_pk_bf16_f32 v166, v96, v97
	v_cvt_pk_bf16_f32 v167, v98, v99
	global_store_dwordx4 v205, v[164:167], s[16:17] offset:256
	v_pk_mul_f32 v[230:231], v[100:101], v[100:101]
	v_pk_fma_f32 v[230:231], v[102:103], v[102:103], v[230:231]
	v_pk_fma_f32 v[230:231], v[96:97], v[96:97], v[230:231]
	v_pk_fma_f32 v[230:231], v[98:99], v[98:99], v[230:231]
	v_pk_add_f32 v[220:221], v[220:221], v[230:231]
	v_add_f32_e32 v213, v220, v221
	s_waitcnt vmcnt(14)
; __device__ __forceinline__ unsigned cvtpk(float lo, float hi) { f32x2_t v = {lo, hi}; bf16x2_t b = __builtin_convertvector(v, bf16x2_t); return __builtin_bit_cast(unsigned, b); }
; __device__ __forceinline__ float bflo(unsigned w) { return __uint_as_float(w << 16); }
; __device__ __forceinline__ float bfhi(unsigned w) { return __uint_as_float(w & 0xffff0000u); }
;     __device__ __forceinline__ void operator()(const f32x4 (&acc)[2][2][4][2], const Unit& u, int wr, int wc, int fr, int fq) const {
;     ...
;                 const int row = row0 + ai * HALF + m * 16; float s = 0.f;
; #pragma unroll
;                 for (int bj = 0; bj < 2; ++bj) {
;                     const size_t off = (size_t)row * DM + col0 + bj * HALF;
;                     f32x4 v0, v1;
;                     if (RM == 0) { v0 = *(const f32x4*)(xf + off); v1 = *(const f32x4*)(xf + off + 4); }
;                     else { const u32x4 w = xv[RM == 0 ? 0 : ai][RM == 0 ? 0 : m][RM == 0 ? 0 : bj]; v0 = (f32x4){bflo(w.x), bfhi(w.x), bflo(w.y), bfhi(w.y)}; v1 = (f32x4){bflo(w.z), bfhi(w.z), bflo(w.w), bfhi(w.w)}; }
;                     v0 = v0 + acc[ai][bj][m][0] * alpha; v1 = v1 + acc[ai][bj][m][1] * alpha;
;                     if (RM == 2) { *(f32x4*)(outf + off) = v0; *(f32x4*)(outf + off + 4) = v1; }
;                     else {
;                         u32x4 w; w.x = cvtpk(v0[0], v0[1]); w.y = cvtpk(v0[2], v0[3]); w.z = cvtpk(v1[0], v1[1]); w.w = cvtpk(v1[2], v1[3]);
;                         *(u32x4*)(xb + off) = w;
;                         s += (v0[0] * v0[0] + v0[1] * v0[1]) + (v0[2] * v0[2] + v0[3] * v0[3]) + (v1[0] * v1[0] + v1[1] * v1[1]) + (v1[2] * v1[2] + v1[3] * v1[3]);
;                     }
;                 }
	v_lshlrev_b32_e32 v222, 16, v168
	v_and_b32_e32 v223, 0xffff0000, v168
	v_lshlrev_b32_e32 v224, 16, v169
	v_and_b32_e32 v225, 0xffff0000, v169
	v_lshlrev_b32_e32 v226, 16, v170
	v_and_b32_e32 v227, 0xffff0000, v170
	v_lshlrev_b32_e32 v228, 16, v171
	v_and_b32_e32 v229, 0xffff0000, v171
	v_pk_add_f32 v[92:93], v[92:93], v[222:223]
	v_pk_add_f32 v[94:95], v[94:95], v[224:225]
	v_pk_add_f32 v[88:89], v[88:89], v[226:227]
	v_pk_add_f32 v[90:91], v[90:91], v[228:229]
	v_cvt_pk_bf16_f32 v168, v92, v93
	v_cvt_pk_bf16_f32 v169, v94, v95
	v_cvt_pk_bf16_f32 v170, v88, v89
	v_cvt_pk_bf16_f32 v171, v90, v91
	global_store_dwordx4 v206, v[168:171], s[16:17]
	v_pk_mul_f32 v[220:221], v[92:93], v[92:93]
	v_pk_fma_f32 v[220:221], v[94:95], v[94:95], v[220:221]
	v_pk_fma_f32 v[220:221], v[88:89], v[88:89], v[220:221]
	v_pk_fma_f32 v[220:221], v[90:91], v[90:91], v[220:221]
	v_lshlrev_b32_e32 v222, 16, v172
	v_and_b32_e32 v223, 0xffff0000, v172
	v_lshlrev_b32_e32 v224, 16, v173
	v_and_b32_e32 v225, 0xffff0000, v173
	v_lshlrev_b32_e32 v226, 16, v174
	v_and_b32_e32 v227, 0xffff0000, v174
	v_lshlrev_b32_e32 v228, 16, v175
	v_and_b32_e32 v229, 0xffff0000, v175
	v_pk_add_f32 v[84:85], v[84:85], v[222:223]
	v_pk_add_f32 v[86:87], v[86:87], v[224:225]
	v_pk_add_f32 v[80:81], v[80:81], v[226:227]
	v_pk_add_f32 v[82:83], v[82:83], v[228:229]
	v_cvt_pk_bf16_f32 v172, v84, v85
	v_cvt_pk_bf16_f32 v173, v86, v87
	v_cvt_pk_bf16_f32 v174, v80, v81
	v_cvt_pk_bf16_f32 v175, v82, v83
	global_store_dwordx4 v206, v[172:175], s[16:17] offset:256
	v_pk_mul_f32 v[230:231], v[84:85], v[84:85]
	v_pk_fma_f32 v[230:231], v[86:87], v[86:87], v[230:231]
	v_pk_fma_f32 v[230:231], v[80:81], v[80:81], v[230:231]
	v_pk_fma_f32 v[230:231], v[82:83], v[82:83], v[230:231]
	v_pk_add_f32 v[220:221], v[220:221], v[230:231]
	v_add_f32_e32 v214, v220, v221
	s_waitcnt vmcnt(14)
	v_lshlrev_b32_e32 v222, 16, v176
	v_and_b32_e32 v223, 0xffff0000, v176
	v_lshlrev_b32_e32 v224, 16, v177
	v_and_b32_e32 v225, 0xffff0000, v177
	v_lshlrev_b32_e32 v226, 16, v178
	v_and_b32_e32 v227, 0xffff0000, v178
	v_lshlrev_b32_e32 v228, 16, v179
	v_and_b32_e32 v229, 0xffff0000, v179
	v_pk_add_f32 v[76:77], v[76:77], v[222:223]
	v_pk_add_f32 v[78:79], v[78:79], v[224:225]
	v_pk_add_f32 v[72:73], v[72:73], v[226:227]
	v_pk_add_f32 v[74:75], v[74:75], v[228:229]
	v_cvt_pk_bf16_f32 v176, v76, v77
	v_cvt_pk_bf16_f32 v177, v78, v79
	v_cvt_pk_bf16_f32 v178, v72, v73
	v_cvt_pk_bf16_f32 v179, v74, v75
	global_store_dwordx4 v207, v[176:179], s[16:17]
	v_pk_mul_f32 v[220:221], v[76:77], v[76:77]
	v_pk_fma_f32 v[220:221], v[78:79], v[78:79], v[220:221]
	v_pk_fma_f32 v[220:221], v[72:73], v[72:73], v[220:221]
	v_pk_fma_f32 v[220:221], v[74:75], v[74:75], v[220:221]
	v_lshlrev_b32_e32 v222, 16, v180
	v_and_b32_e32 v223, 0xffff0000, v180
	v_lshlrev_b32_e32 v224, 16, v181
	v_and_b32_e32 v225, 0xffff0000, v181
	v_lshlrev_b32_e32 v226, 16, v182
	v_and_b32_e32 v227, 0xffff0000, v182
	v_lshlrev_b32_e32 v228, 16, v183
	v_and_b32_e32 v229, 0xffff0000, v183
	v_pk_add_f32 v[68:69], v[68:69], v[222:223]
	v_pk_add_f32 v[70:71], v[70:71], v[224:225]
	v_pk_add_f32 v[64:65], v[64:65], v[226:227]
	v_pk_add_f32 v[66:67], v[66:67], v[228:229]
	v_cvt_pk_bf16_f32 v180, v68, v69
	v_cvt_pk_bf16_f32 v181, v70, v71
	v_cvt_pk_bf16_f32 v182, v64, v65
	v_cvt_pk_bf16_f32 v183, v66, v67
	global_store_dwordx4 v207, v[180:183], s[16:17] offset:256
	v_pk_mul_f32 v[230:231], v[68:69], v[68:69]
	v_pk_fma_f32 v[230:231], v[70:71], v[70:71], v[230:231]
	v_pk_fma_f32 v[230:231], v[64:65], v[64:65], v[230:231]
	v_pk_fma_f32 v[230:231], v[66:67], v[66:67], v[230:231]
	v_pk_add_f32 v[220:221], v[220:221], v[230:231]
	v_add_f32_e32 v215, v220, v221
	s_waitcnt vmcnt(14)
	v_lshlrev_b32_e32 v222, 16, v184
	v_and_b32_e32 v223, 0xffff0000, v184
	v_lshlrev_b32_e32 v224, 16, v185
	v_and_b32_e32 v225, 0xffff0000, v185
	v_lshlrev_b32_e32 v226, 16, v186
	v_and_b32_e32 v227, 0xffff0000, v186
	v_lshlrev_b32_e32 v228, 16, v187
	v_and_b32_e32 v229, 0xffff0000, v187
	v_pk_add_f32 v[60:61], v[60:61], v[222:223]
	v_pk_add_f32 v[62:63], v[62:63], v[224:225]
	v_pk_add_f32 v[56:57], v[56:57], v[226:227]
	v_pk_add_f32 v[58:59], v[58:59], v[228:229]
	v_cvt_pk_bf16_f32 v184, v60, v61
	v_cvt_pk_bf16_f32 v185, v62, v63
	v_cvt_pk_bf16_f32 v186, v56, v57
	v_cvt_pk_bf16_f32 v187, v58, v59
	global_store_dwordx4 v208, v[184:187], s[16:17]
	v_pk_mul_f32 v[220:221], v[60:61], v[60:61]
	v_pk_fma_f32 v[220:221], v[62:63], v[62:63], v[220:221]
	v_pk_fma_f32 v[220:221], v[56:57], v[56:57], v[220:221]
	v_pk_fma_f32 v[220:221], v[58:59], v[58:59], v[220:221]
	v_lshlrev_b32_e32 v222, 16, v188
	v_and_b32_e32 v223, 0xffff0000, v188
	v_lshlrev_b32_e32 v224, 16, v189
	v_and_b32_e32 v225, 0xffff0000, v189
	v_lshlrev_b32_e32 v226, 16, v190
	v_and_b32_e32 v227, 0xffff0000, v190
	v_lshlrev_b32_e32 v228, 16, v191
	v_and_b32_e32 v229, 0xffff0000, v191
	v_pk_add_f32 v[52:53], v[52:53], v[222:223]
	v_pk_add_f32 v[54:55], v[54:55], v[224:225]
	v_pk_add_f32 v[48:49], v[48:49], v[226:227]
	v_pk_add_f32 v[50:51], v[50:51], v[228:229]
	v_cvt_pk_bf16_f32 v188, v52, v53
	v_cvt_pk_bf16_f32 v189, v54, v55
	v_cvt_pk_bf16_f32 v190, v48, v49
	v_cvt_pk_bf16_f32 v191, v50, v51
	global_store_dwordx4 v208, v[188:191], s[16:17] offset:256
	v_pk_mul_f32 v[230:231], v[52:53], v[52:53]
	v_pk_fma_f32 v[230:231], v[54:55], v[54:55], v[230:231]
	v_pk_fma_f32 v[230:231], v[48:49], v[48:49], v[230:231]
	v_pk_fma_f32 v[230:231], v[50:51], v[50:51], v[230:231]
	v_pk_add_f32 v[220:221], v[220:221], v[230:231]
	v_add_f32_e32 v216, v220, v221
	s_waitcnt vmcnt(14)
; __device__ __forceinline__ unsigned cvtpk(float lo, float hi) { f32x2_t v = {lo, hi}; bf16x2_t b = __builtin_convertvector(v, bf16x2_t); return __builtin_bit_cast(unsigned, b); }
; __device__ __forceinline__ float bflo(unsigned w) { return __uint_as_float(w << 16); }
; template <class Epi>
; __device__ __forceinline__ void gemm_phase(LAS unsigned char* lds, const Gemm g, const StaticOrder& S, const Epi& E, int wave_s) {
;     ...
;         if (wr == 0) PG8_BAR;
;         E(acc, cur, wr, wc, fr, fq);
;         if (!has_next) break;
; #pragma unroll
;         for (int a = 0; a < 2; ++a)
; #pragma unroll
;             for (int b = 0; b < 2; ++b)
; #pragma unroll
;                 for (int m = 0; m < 4; ++m)
; #pragma unroll
;                     for (int n = 0; n < 2; ++n) acc[a][b][m][n] = (f32x4){0.f, 0.f, 0.f, 0.f};
;         cur = nxt; cA = nA; cB = nB; ++ui;
;         if (wr == 1) PG8_BAR;
;     __device__ __forceinline__ void operator()(const f32x4 (&acc)[2][2][4][2], const Unit& u, int wr, int wc, int fr, int fq) const {
;     ...
;                 const int row = row0 + ai * HALF + m * 16; float s = 0.f;
; #pragma unroll
;                 for (int bj = 0; bj < 2; ++bj) {
;                     const size_t off = (size_t)row * DM + col0 + bj * HALF;
;                     f32x4 v0, v1;
;                     if (RM == 0) { v0 = *(const f32x4*)(xf + off); v1 = *(const f32x4*)(xf + off + 4); }
;                     else { const u32x4 w = xv[RM == 0 ? 0 : ai][RM == 0 ? 0 : m][RM == 0 ? 0 : bj]; v0 = (f32x4){bflo(w.x), bfhi(w.x), bflo(w.y), bfhi(w.y)}; v1 = (f32x4){bflo(w.z), bfhi(w.z), bflo(w.w), bfhi(w.w)}; }
;                     v0 = v0 + acc[ai][bj][m][0] * alpha; v1 = v1 + acc[ai][bj][m][1] * alpha;
;                     if (RM == 2) { *(f32x4*)(outf + off) = v0; *(f32x4*)(outf + off + 4) = v1; }
;                     else {
;                         u32x4 w; w.x = cvtpk(v0[0], v0[1]); w.y = cvtpk(v0[2], v0[3]); w.z = cvtpk(v1[0], v1[1]); w.w = cvtpk(v1[2], v1[3]);
;                         *(u32x4*)(xb + off) = w;
;                         s += (v0[0] * v0[0] + v0[1] * v0[1]) + (v0[2] * v0[2] + v0[3] * v0[3]) + (v1[0] * v1[0] + v1[1] * v1[1]) + (v1[2] * v1[2] + v1[3] * v1[3]);
;                     }
;                 }
;                 if (RM != 2) { s += __shfl_xor(s, 16); s += __shfl_xor(s, 32); if (fq == 0) ssq_out[(size_t)row * 16 + u.pn * 4 + wc] = s; }
	v_lshlrev_b32_e32 v222, 16, v120
	v_and_b32_e32 v223, 0xffff0000, v120
	v_lshlrev_b32_e32 v224, 16, v121
	v_and_b32_e32 v225, 0xffff0000, v121
	v_lshlrev_b32_e32 v226, 16, v122
	v_and_b32_e32 v227, 0xffff0000, v122
	v_lshlrev_b32_e32 v228, 16, v123
	v_and_b32_e32 v229, 0xffff0000, v123
	v_pk_add_f32 v[44:45], v[44:45], v[222:223]
	v_pk_add_f32 v[46:47], v[46:47], v[224:225]
	v_pk_add_f32 v[40:41], v[40:41], v[226:227]
	v_pk_add_f32 v[42:43], v[42:43], v[228:229]
	v_cvt_pk_bf16_f32 v120, v44, v45
	v_cvt_pk_bf16_f32 v121, v46, v47
	v_cvt_pk_bf16_f32 v122, v40, v41
	v_cvt_pk_bf16_f32 v123, v42, v43
	global_store_dwordx4 v209, v[120:123], s[16:17]
	v_pk_mul_f32 v[220:221], v[44:45], v[44:45]
	v_pk_fma_f32 v[220:221], v[46:47], v[46:47], v[220:221]
	v_pk_fma_f32 v[220:221], v[40:41], v[40:41], v[220:221]
	v_pk_fma_f32 v[220:221], v[42:43], v[42:43], v[220:221]
	v_lshlrev_b32_e32 v222, 16, v124
	v_and_b32_e32 v223, 0xffff0000, v124
	v_lshlrev_b32_e32 v224, 16, v125
	v_and_b32_e32 v225, 0xffff0000, v125
	v_lshlrev_b32_e32 v226, 16, v126
	v_and_b32_e32 v227, 0xffff0000, v126
	v_lshlrev_b32_e32 v228, 16, v127
	v_and_b32_e32 v229, 0xffff0000, v127
	v_pk_add_f32 v[36:37], v[36:37], v[222:223]
	v_pk_add_f32 v[38:39], v[38:39], v[224:225]
	v_pk_add_f32 v[32:33], v[32:33], v[226:227]
	v_pk_add_f32 v[34:35], v[34:35], v[228:229]
	v_cvt_pk_bf16_f32 v124, v36, v37
	v_cvt_pk_bf16_f32 v125, v38, v39
	v_cvt_pk_bf16_f32 v126, v32, v33
	v_cvt_pk_bf16_f32 v127, v34, v35
	global_store_dwordx4 v209, v[124:127], s[16:17] offset:256
	v_pk_mul_f32 v[230:231], v[36:37], v[36:37]
	v_pk_fma_f32 v[230:231], v[38:39], v[38:39], v[230:231]
	v_pk_fma_f32 v[230:231], v[32:33], v[32:33], v[230:231]
	v_pk_fma_f32 v[230:231], v[34:35], v[34:35], v[230:231]
	v_pk_add_f32 v[220:221], v[220:221], v[230:231]
	v_add_f32_e32 v217, v220, v221
	s_waitcnt vmcnt(14)
	v_lshlrev_b32_e32 v222, 16, v128
	v_and_b32_e32 v223, 0xffff0000, v128
	v_lshlrev_b32_e32 v224, 16, v129
	v_and_b32_e32 v225, 0xffff0000, v129
	v_lshlrev_b32_e32 v226, 16, v130
	v_and_b32_e32 v227, 0xffff0000, v130
	v_lshlrev_b32_e32 v228, 16, v131
	v_and_b32_e32 v229, 0xffff0000, v131
	v_pk_add_f32 v[28:29], v[28:29], v[222:223]
	v_pk_add_f32 v[30:31], v[30:31], v[224:225]
	v_pk_add_f32 v[24:25], v[24:25], v[226:227]
	v_pk_add_f32 v[26:27], v[26:27], v[228:229]
	v_cvt_pk_bf16_f32 v128, v28, v29
	v_cvt_pk_bf16_f32 v129, v30, v31
	v_cvt_pk_bf16_f32 v130, v24, v25
	v_cvt_pk_bf16_f32 v131, v26, v27
	global_store_dwordx4 v210, v[128:131], s[16:17]
	v_pk_mul_f32 v[220:221], v[28:29], v[28:29]
	v_pk_fma_f32 v[220:221], v[30:31], v[30:31], v[220:221]
	v_pk_fma_f32 v[220:221], v[24:25], v[24:25], v[220:221]
	v_pk_fma_f32 v[220:221], v[26:27], v[26:27], v[220:221]
	v_lshlrev_b32_e32 v222, 16, v132
	v_and_b32_e32 v223, 0xffff0000, v132
	v_lshlrev_b32_e32 v224, 16, v133
	v_and_b32_e32 v225, 0xffff0000, v133
	v_lshlrev_b32_e32 v226, 16, v134
	v_and_b32_e32 v227, 0xffff0000, v134
	v_lshlrev_b32_e32 v228, 16, v135
	v_and_b32_e32 v229, 0xffff0000, v135
	v_pk_add_f32 v[20:21], v[20:21], v[222:223]
	v_pk_add_f32 v[22:23], v[22:23], v[224:225]
	v_pk_add_f32 v[16:17], v[16:17], v[226:227]
	v_pk_add_f32 v[18:19], v[18:19], v[228:229]
	v_cvt_pk_bf16_f32 v132, v20, v21
	v_cvt_pk_bf16_f32 v133, v22, v23
	v_cvt_pk_bf16_f32 v134, v16, v17
	v_cvt_pk_bf16_f32 v135, v18, v19
	global_store_dwordx4 v210, v[132:135], s[16:17] offset:256
	v_pk_mul_f32 v[230:231], v[20:21], v[20:21]
	v_pk_fma_f32 v[230:231], v[22:23], v[22:23], v[230:231]
	v_pk_fma_f32 v[230:231], v[16:17], v[16:17], v[230:231]
	v_pk_fma_f32 v[230:231], v[18:19], v[18:19], v[230:231]
	v_pk_add_f32 v[220:221], v[220:221], v[230:231]
	v_add_f32_e32 v218, v220, v221
	s_waitcnt vmcnt(14)
	v_lshlrev_b32_e32 v222, 16, v136
	v_and_b32_e32 v223, 0xffff0000, v136
	v_lshlrev_b32_e32 v224, 16, v137
	v_and_b32_e32 v225, 0xffff0000, v137
	v_lshlrev_b32_e32 v226, 16, v138
	v_and_b32_e32 v227, 0xffff0000, v138
	v_lshlrev_b32_e32 v228, 16, v139
	v_and_b32_e32 v229, 0xffff0000, v139
	v_pk_add_f32 v[12:13], v[12:13], v[222:223]
	v_pk_add_f32 v[14:15], v[14:15], v[224:225]
	v_pk_add_f32 v[8:9], v[8:9], v[226:227]
	v_pk_add_f32 v[10:11], v[10:11], v[228:229]
	v_cvt_pk_bf16_f32 v136, v12, v13
	v_cvt_pk_bf16_f32 v137, v14, v15
	v_cvt_pk_bf16_f32 v138, v8, v9
	v_cvt_pk_bf16_f32 v139, v10, v11
	global_store_dwordx4 v211, v[136:139], s[16:17]
	v_pk_mul_f32 v[220:221], v[12:13], v[12:13]
	v_pk_fma_f32 v[220:221], v[14:15], v[14:15], v[220:221]
	v_pk_fma_f32 v[220:221], v[8:9], v[8:9], v[220:221]
	v_pk_fma_f32 v[220:221], v[10:11], v[10:11], v[220:221]
	v_lshlrev_b32_e32 v222, 16, v140
	v_and_b32_e32 v223, 0xffff0000, v140
	v_lshlrev_b32_e32 v224, 16, v141
	v_and_b32_e32 v225, 0xffff0000, v141
	v_lshlrev_b32_e32 v226, 16, v142
	v_and_b32_e32 v227, 0xffff0000, v142
	v_lshlrev_b32_e32 v228, 16, v143
	v_and_b32_e32 v229, 0xffff0000, v143
	v_pk_add_f32 v[4:5], v[4:5], v[222:223]
	v_pk_add_f32 v[6:7], v[6:7], v[224:225]
	v_pk_add_f32 v[0:1], v[0:1], v[226:227]
	v_pk_add_f32 v[2:3], v[2:3], v[228:229]
	v_cvt_pk_bf16_f32 v140, v4, v5
	v_cvt_pk_bf16_f32 v141, v6, v7
	v_cvt_pk_bf16_f32 v142, v0, v1
	v_cvt_pk_bf16_f32 v143, v2, v3
	global_store_dwordx4 v211, v[140:143], s[16:17] offset:256
	v_pk_mul_f32 v[230:231], v[4:5], v[4:5]
	v_pk_fma_f32 v[230:231], v[6:7], v[6:7], v[230:231]
	v_pk_fma_f32 v[230:231], v[0:1], v[0:1], v[230:231]
	v_pk_fma_f32 v[230:231], v[2:3], v[2:3], v[230:231]
	v_pk_add_f32 v[220:221], v[220:221], v[230:231]
	v_add_f32_e32 v219, v220, v221
	s_nop 1
	v_permlane32_swap_b32_e32 v212, v213
	v_permlane32_swap_b32_e32 v214, v215
	v_permlane32_swap_b32_e32 v216, v217
	v_permlane32_swap_b32_e32 v218, v219
	v_add_f32_e32 v212, v212, v213
	v_add_f32_e32 v214, v214, v215
	v_add_f32_e32 v216, v216, v217
	v_add_f32_e32 v218, v218, v219
	s_nop 1
	v_permlane16_swap_b32_e32 v212, v214
	v_permlane16_swap_b32_e32 v216, v218
	v_add_f32_e32 v212, v212, v214
	v_add_f32_e32 v216, v216, v218
	global_store_dword v236, v212, s[18:19]
	global_store_dword v237, v216, s[18:19]
	s_andn2_b64 vcc, exec, s[8:9]
	s_mov_b64 s[8:9], -1
	s_cbranch_vccnz .LBB0_706
	s_andn2_b64 vcc, exec, s[14:15]
	s_cbranch_vccnz .LBB0_705
	s_barrier
	s_branch .LBB0_705

; __device__ __forceinline__ unsigned cvtpk(float lo, float hi) { f32x2_t v = {lo, hi}; bf16x2_t b = __builtin_convertvector(v, bf16x2_t); return __builtin_bit_cast(unsigned, b); }
;     __device__ __forceinline__ void operator()(const f32x4 (&acc)[2][2][4][2], const Unit& u, int wr, int wc, int fr, int fq) const {
;         const int row0 = u.pm * BM + wr * 64 + fr, col0 = u.pn * BM + wc * 32 + 8 * fq;
;         u32x4 xv[RM == 0 ? 1 : 2][RM == 0 ? 1 : 4][RM == 0 ? 1 : 2];
;         if (RM != 0) {
; #pragma unroll
;             for (int ai = 0; ai < 2; ++ai)
; #pragma unroll
;                 for (int m = 0; m < 4; ++m)
; #pragma unroll
;                     for (int bj = 0; bj < 2; ++bj) xv[RM == 0 ? 0 : ai][RM == 0 ? 0 : m][RM == 0 ? 0 : bj] = *(const u32x4*)(xb + (size_t)(row0 + ai * HALF + m * 16) * DM + col0 + bj * HALF);
;         }
; #pragma unroll
;         for (int ai = 0; ai < 2; ++ai)
; #pragma unroll
;             for (int m = 0; m < 4; ++m) {
;                 const int row = row0 + ai * HALF + m * 16; float s = 0.f;
; #pragma unroll
;                 for (int bj = 0; bj < 2; ++bj) {
;                     const size_t off = (size_t)row * DM + col0 + bj * HALF;
;                     f32x4 v0, v1;
;                     if (RM == 0) { v0 = *(const f32x4*)(xf + off); v1 = *(const f32x4*)(xf + off + 4); }
;                     else { const u32x4 w = xv[RM == 0 ? 0 : ai][RM == 0 ? 0 : m][RM == 0 ? 0 : bj]; v0 = (f32x4){bflo(w.x), bfhi(w.x), bflo(w.y), bfhi(w.y)}; v1 = (f32x4){bflo(w.z), bfhi(w.z), bflo(w.w), bfhi(w.w)}; }
;                     v0 = v0 + acc[ai][bj][m][0] * alpha; v1 = v1 + acc[ai][bj][m][1] * alpha;
;                     if (RM == 2) { *(f32x4*)(outf + off) = v0; *(f32x4*)(outf + off + 4) = v1; }
;                     else {
;                         u32x4 w; w.x = cvtpk(v0[0], v0[1]); w.y = cvtpk(v0[2], v0[3]); w.z = cvtpk(v1[0], v1[1]); w.w = cvtpk(v1[2], v1[3]);
;                         *(u32x4*)(xb + off) = w;
;                         s += (v0[0] * v0[0] + v0[1] * v0[1]) + (v0[2] * v0[2] + v0[3] * v0[3]) + (v1[0] * v1[0] + v1[1] * v1[1]) + (v1[2] * v1[2] + v1[3] * v1[3]);
;                     }
;                 }
;                 if (RM != 2) { s += __shfl_xor(s, 16); s += __shfl_xor(s, 32); if (fq == 0) ssq_out[(size_t)row * 16 + u.pn * 4 + wc] = s; }
.LBB0_1141:
	v_lshl_or_b32 v232, s14, 8, v242
	v_lshl_add_u32 v233, s51, 8, v240
	v_lshlrev_b32_e32 v204, 11, v233
	v_lshl_add_u32 v204, v232, 1, v204
	v_add_u32_e32 v205, 0x8000, v204
	v_add_u32_e32 v206, 0x10000, v204
	v_add_u32_e32 v207, 0x18000, v204
	v_add_u32_e32 v208, 0x40000, v204
	v_add_u32_e32 v209, 0x48000, v204
	v_add_u32_e32 v210, 0x50000, v204
	v_add_u32_e32 v211, 0x58000, v204
	global_load_dwordx4 v[152:155], v204, s[18:19]
	global_load_dwordx4 v[156:159], v204, s[18:19] offset:256
	global_load_dwordx4 v[160:163], v205, s[18:19]
	global_load_dwordx4 v[164:167], v205, s[18:19] offset:256
	global_load_dwordx4 v[168:171], v206, s[18:19]
	global_load_dwordx4 v[172:175], v206, s[18:19] offset:256
	global_load_dwordx4 v[176:179], v207, s[18:19]
	global_load_dwordx4 v[180:183], v207, s[18:19] offset:256
	global_load_dwordx4 v[184:187], v208, s[18:19]
	global_load_dwordx4 v[188:191], v208, s[18:19] offset:256
	global_load_dwordx4 v[120:123], v209, s[18:19]
	global_load_dwordx4 v[124:127], v209, s[18:19] offset:256
	global_load_dwordx4 v[128:131], v210, s[18:19]
	global_load_dwordx4 v[132:135], v210, s[18:19] offset:256
	global_load_dwordx4 v[136:139], v211, s[18:19]
	global_load_dwordx4 v[140:143], v211, s[18:19] offset:256
	v_mbcnt_lo_u32_b32 v234, -1, 0
	v_mbcnt_hi_u32_b32 v234, -1, v234
	v_lshrrev_b32_e32 v235, 4, v234
	v_and_b32_e32 v236, 1, v235
	v_lshlrev_b32_e32 v236, 5, v236
	v_lshrrev_b32_e32 v235, 1, v235
	v_lshl_add_u32 v236, v235, 4, v236
	v_add_u32_e32 v236, v233, v236
	v_lshlrev_b32_e32 v236, 6, v236
	s_lshl_b32 s30, s14, 4
	s_lshl_b32 s31, s40, 2
	s_add_u32 s30, s30, s31
	v_add_u32_e32 v236, s30, v236
	v_add_u32_e32 v237, 0x2000, v236
	s_waitcnt vmcnt(14)
	v_lshlrev_b32_e32 v222, 16, v152
	v_and_b32_e32 v223, 0xffff0000, v152
	v_lshlrev_b32_e32 v224, 16, v153
	v_and_b32_e32 v225, 0xffff0000, v153
	v_lshlrev_b32_e32 v226, 16, v154
	v_and_b32_e32 v227, 0xffff0000, v154
	v_lshlrev_b32_e32 v228, 16, v155
	v_and_b32_e32 v229, 0xffff0000, v155
	v_pk_fma_f32 v[148:149], v[148:149], 0.5, v[222:223] op_sel_hi:[1,0,1]
	v_pk_fma_f32 v[150:151], v[150:151], 0.5, v[224:225] op_sel_hi:[1,0,1]
	v_pk_fma_f32 v[144:145], v[144:145], 0.5, v[226:227] op_sel_hi:[1,0,1]
	v_pk_fma_f32 v[146:147], v[146:147], 0.5, v[228:229] op_sel_hi:[1,0,1]
	v_cvt_pk_bf16_f32 v152, v148, v149
	v_cvt_pk_bf16_f32 v153, v150, v151
	v_cvt_pk_bf16_f32 v154, v144, v145
	v_cvt_pk_bf16_f32 v155, v146, v147
	global_store_dwordx4 v204, v[152:155], s[18:19]
	v_pk_mul_f32 v[220:221], v[148:149], v[148:149]
	v_pk_fma_f32 v[220:221], v[150:151], v[150:151], v[220:221]
	v_pk_fma_f32 v[220:221], v[144:145], v[144:145], v[220:221]
	v_pk_fma_f32 v[220:221], v[146:147], v[146:147], v[220:221]
	v_lshlrev_b32_e32 v222, 16, v156
	v_and_b32_e32 v223, 0xffff0000, v156
	v_lshlrev_b32_e32 v224, 16, v157
	v_and_b32_e32 v225, 0xffff0000, v157
	v_lshlrev_b32_e32 v226, 16, v158
	v_and_b32_e32 v227, 0xffff0000, v158
	v_lshlrev_b32_e32 v228, 16, v159
	v_and_b32_e32 v229, 0xffff0000, v159
	v_pk_fma_f32 v[116:117], v[116:117], 0.5, v[222:223] op_sel_hi:[1,0,1]
	v_pk_fma_f32 v[118:119], v[118:119], 0.5, v[224:225] op_sel_hi:[1,0,1]
	v_pk_fma_f32 v[112:113], v[112:113], 0.5, v[226:227] op_sel_hi:[1,0,1]
	v_pk_fma_f32 v[114:115], v[114:115], 0.5, v[228:229] op_sel_hi:[1,0,1]
	v_cvt_pk_bf16_f32 v156, v116, v117
	v_cvt_pk_bf16_f32 v157, v118, v119
	v_cvt_pk_bf16_f32 v158, v112, v113
	v_cvt_pk_bf16_f32 v159, v114, v115
	global_store_dwordx4 v204, v[156:159], s[18:19] offset:256
	v_pk_mul_f32 v[230:231], v[116:117], v[116:117]
	v_pk_fma_f32 v[230:231], v[118:119], v[118:119], v[230:231]
	v_pk_fma_f32 v[230:231], v[112:113], v[112:113], v[230:231]
	v_pk_fma_f32 v[230:231], v[114:115], v[114:115], v[230:231]
	v_pk_add_f32 v[220:221], v[220:221], v[230:231]
	v_add_f32_e32 v212, v220, v221
	s_waitcnt vmcnt(14)
	v_lshlrev_b32_e32 v222, 16, v160
	v_and_b32_e32 v223, 0xffff0000, v160
	v_lshlrev_b32_e32 v224, 16, v161
	v_and_b32_e32 v225, 0xffff0000, v161
	v_lshlrev_b32_e32 v226, 16, v162
	v_and_b32_e32 v227, 0xffff0000, v162
	v_lshlrev_b32_e32 v228, 16, v163
	v_and_b32_e32 v229, 0xffff0000, v163
	v_pk_fma_f32 v[108:109], v[108:109], 0.5, v[222:223] op_sel_hi:[1,0,1]
	v_pk_fma_f32 v[110:111], v[110:111], 0.5, v[224:225] op_sel_hi:[1,0,1]
	v_pk_fma_f32 v[104:105], v[104:105], 0.5, v[226:227] op_sel_hi:[1,0,1]
	v_pk_fma_f32 v[106:107], v[106:107], 0.5, v[228:229] op_sel_hi:[1,0,1]
	v_cvt_pk_bf16_f32 v160, v108, v109
	v_cvt_pk_bf16_f32 v161, v110, v111
	v_cvt_pk_bf16_f32 v162, v104, v105
	v_cvt_pk_bf16_f32 v163, v106, v107
	global_store_dwordx4 v205, v[160:163], s[18:19]
	v_pk_mul_f32 v[220:221], v[108:109], v[108:109]
	v_pk_fma_f32 v[220:221], v[110:111], v[110:111], v[220:221]
	v_pk_fma_f32 v[220:221], v[104:105], v[104:105], v[220:221]
	v_pk_fma_f32 v[220:221], v[106:107], v[106:107], v[220:221]
	v_lshlrev_b32_e32 v222, 16, v164
	v_and_b32_e32 v223, 0xffff0000, v164
	v_lshlrev_b32_e32 v224, 16, v165
	v_and_b32_e32 v225, 0xffff0000, v165
	v_lshlrev_b32_e32 v226, 16, v166
	v_and_b32_e32 v227, 0xffff0000, v166
	v_lshlrev_b32_e32 v228, 16, v167
	v_and_b32_e32 v229, 0xffff0000, v167
	v_pk_fma_f32 v[100:101], v[100:101], 0.5, v[222:223] op_sel_hi:[1,0,1]
	v_pk_fma_f32 v[102:103], v[102:103], 0.5, v[224:225] op_sel_hi:[1,0,1]
	v_pk_fma_f32 v[96:97], v[96:97], 0.5, v[226:227] op_sel_hi:[1,0,1]
	v_pk_fma_f32 v[98:99], v[98:99], 0.5, v[228:229] op_sel_hi:[1,0,1]
	v_cvt_pk_bf16_f32 v164, v100, v101
	v_cvt_pk_bf16_f32 v165, v102, v103
	v_cvt_pk_bf16_f32 v166, v96, v97
	v_cvt_pk_bf16_f32 v167, v98, v99
	global_store_dwordx4 v205, v[164:167], s[18:19] offset:256
	v_pk_mul_f32 v[230:231], v[100:101], v[100:101]
	v_pk_fma_f32 v[230:231], v[102:103], v[102:103], v[230:231]
	v_pk_fma_f32 v[230:231], v[96:97], v[96:97], v[230:231]
	v_pk_fma_f32 v[230:231], v[98:99], v[98:99], v[230:231]
	v_pk_add_f32 v[220:221], v[220:221], v[230:231]
	v_add_f32_e32 v213, v220, v221
	s_waitcnt vmcnt(14)
; __device__ __forceinline__ unsigned cvtpk(float lo, float hi) { f32x2_t v = {lo, hi}; bf16x2_t b = __builtin_convertvector(v, bf16x2_t); return __builtin_bit_cast(unsigned, b); }
; __device__ __forceinline__ float bflo(unsigned w) { return __uint_as_float(w << 16); }
; __device__ __forceinline__ float bfhi(unsigned w) { return __uint_as_float(w & 0xffff0000u); }
;     __device__ __forceinline__ void operator()(const f32x4 (&acc)[2][2][4][2], const Unit& u, int wr, int wc, int fr, int fq) const {
;     ...
;                 const int row = row0 + ai * HALF + m * 16; float s = 0.f;
; #pragma unroll
;                 for (int bj = 0; bj < 2; ++bj) {
;                     const size_t off = (size_t)row * DM + col0 + bj * HALF;
;                     f32x4 v0, v1;
;                     if (RM == 0) { v0 = *(const f32x4*)(xf + off); v1 = *(const f32x4*)(xf + off + 4); }
;                     else { const u32x4 w = xv[RM == 0 ? 0 : ai][RM == 0 ? 0 : m][RM == 0 ? 0 : bj]; v0 = (f32x4){bflo(w.x), bfhi(w.x), bflo(w.y), bfhi(w.y)}; v1 = (f32x4){bflo(w.z), bfhi(w.z), bflo(w.w), bfhi(w.w)}; }
;                     v0 = v0 + acc[ai][bj][m][0] * alpha; v1 = v1 + acc[ai][bj][m][1] * alpha;
;                     if (RM == 2) { *(f32x4*)(outf + off) = v0; *(f32x4*)(outf + off + 4) = v1; }
;                     else {
;                         u32x4 w; w.x = cvtpk(v0[0], v0[1]); w.y = cvtpk(v0[2], v0[3]); w.z = cvtpk(v1[0], v1[1]); w.w = cvtpk(v1[2], v1[3]);
;                         *(u32x4*)(xb + off) = w;
;                         s += (v0[0] * v0[0] + v0[1] * v0[1]) + (v0[2] * v0[2] + v0[3] * v0[3]) + (v1[0] * v1[0] + v1[1] * v1[1]) + (v1[2] * v1[2] + v1[3] * v1[3]);
;                     }
;                 }
	v_lshlrev_b32_e32 v222, 16, v168
	v_and_b32_e32 v223, 0xffff0000, v168
	v_lshlrev_b32_e32 v224, 16, v169
	v_and_b32_e32 v225, 0xffff0000, v169
	v_lshlrev_b32_e32 v226, 16, v170
	v_and_b32_e32 v227, 0xffff0000, v170
	v_lshlrev_b32_e32 v228, 16, v171
	v_and_b32_e32 v229, 0xffff0000, v171
	v_pk_fma_f32 v[92:93], v[92:93], 0.5, v[222:223] op_sel_hi:[1,0,1]
	v_pk_fma_f32 v[94:95], v[94:95], 0.5, v[224:225] op_sel_hi:[1,0,1]
	v_pk_fma_f32 v[88:89], v[88:89], 0.5, v[226:227] op_sel_hi:[1,0,1]
	v_pk_fma_f32 v[90:91], v[90:91], 0.5, v[228:229] op_sel_hi:[1,0,1]
	v_cvt_pk_bf16_f32 v168, v92, v93
	v_cvt_pk_bf16_f32 v169, v94, v95
	v_cvt_pk_bf16_f32 v170, v88, v89
	v_cvt_pk_bf16_f32 v171, v90, v91
	global_store_dwordx4 v206, v[168:171], s[18:19]
	v_pk_mul_f32 v[220:221], v[92:93], v[92:93]
	v_pk_fma_f32 v[220:221], v[94:95], v[94:95], v[220:221]
	v_pk_fma_f32 v[220:221], v[88:89], v[88:89], v[220:221]
	v_pk_fma_f32 v[220:221], v[90:91], v[90:91], v[220:221]
	v_lshlrev_b32_e32 v222, 16, v172
	v_and_b32_e32 v223, 0xffff0000, v172
	v_lshlrev_b32_e32 v224, 16, v173
	v_and_b32_e32 v225, 0xffff0000, v173
	v_lshlrev_b32_e32 v226, 16, v174
	v_and_b32_e32 v227, 0xffff0000, v174
	v_lshlrev_b32_e32 v228, 16, v175
	v_and_b32_e32 v229, 0xffff0000, v175
	v_pk_fma_f32 v[84:85], v[84:85], 0.5, v[222:223] op_sel_hi:[1,0,1]
	v_pk_fma_f32 v[86:87], v[86:87], 0.5, v[224:225] op_sel_hi:[1,0,1]
	v_pk_fma_f32 v[80:81], v[80:81], 0.5, v[226:227] op_sel_hi:[1,0,1]
	v_pk_fma_f32 v[82:83], v[82:83], 0.5, v[228:229] op_sel_hi:[1,0,1]
	v_cvt_pk_bf16_f32 v172, v84, v85
	v_cvt_pk_bf16_f32 v173, v86, v87
	v_cvt_pk_bf16_f32 v174, v80, v81
	v_cvt_pk_bf16_f32 v175, v82, v83
	global_store_dwordx4 v206, v[172:175], s[18:19] offset:256
	v_pk_mul_f32 v[230:231], v[84:85], v[84:85]
	v_pk_fma_f32 v[230:231], v[86:87], v[86:87], v[230:231]
	v_pk_fma_f32 v[230:231], v[80:81], v[80:81], v[230:231]
	v_pk_fma_f32 v[230:231], v[82:83], v[82:83], v[230:231]
	v_pk_add_f32 v[220:221], v[220:221], v[230:231]
	v_add_f32_e32 v214, v220, v221
	s_waitcnt vmcnt(14)
	v_lshlrev_b32_e32 v222, 16, v176
	v_and_b32_e32 v223, 0xffff0000, v176
	v_lshlrev_b32_e32 v224, 16, v177
	v_and_b32_e32 v225, 0xffff0000, v177
	v_lshlrev_b32_e32 v226, 16, v178
	v_and_b32_e32 v227, 0xffff0000, v178
	v_lshlrev_b32_e32 v228, 16, v179
	v_and_b32_e32 v229, 0xffff0000, v179
	v_pk_fma_f32 v[76:77], v[76:77], 0.5, v[222:223] op_sel_hi:[1,0,1]
	v_pk_fma_f32 v[78:79], v[78:79], 0.5, v[224:225] op_sel_hi:[1,0,1]
	v_pk_fma_f32 v[72:73], v[72:73], 0.5, v[226:227] op_sel_hi:[1,0,1]
	v_pk_fma_f32 v[74:75], v[74:75], 0.5, v[228:229] op_sel_hi:[1,0,1]
	v_cvt_pk_bf16_f32 v176, v76, v77
	v_cvt_pk_bf16_f32 v177, v78, v79
	v_cvt_pk_bf16_f32 v178, v72, v73
	v_cvt_pk_bf16_f32 v179, v74, v75
	global_store_dwordx4 v207, v[176:179], s[18:19]
	v_pk_mul_f32 v[220:221], v[76:77], v[76:77]
	v_pk_fma_f32 v[220:221], v[78:79], v[78:79], v[220:221]
	v_pk_fma_f32 v[220:221], v[72:73], v[72:73], v[220:221]
	v_pk_fma_f32 v[220:221], v[74:75], v[74:75], v[220:221]
	v_lshlrev_b32_e32 v222, 16, v180
	v_and_b32_e32 v223, 0xffff0000, v180
	v_lshlrev_b32_e32 v224, 16, v181
	v_and_b32_e32 v225, 0xffff0000, v181
	v_lshlrev_b32_e32 v226, 16, v182
	v_and_b32_e32 v227, 0xffff0000, v182
	v_lshlrev_b32_e32 v228, 16, v183
	v_and_b32_e32 v229, 0xffff0000, v183
	v_pk_fma_f32 v[68:69], v[68:69], 0.5, v[222:223] op_sel_hi:[1,0,1]
	v_pk_fma_f32 v[70:71], v[70:71], 0.5, v[224:225] op_sel_hi:[1,0,1]
	v_pk_fma_f32 v[64:65], v[64:65], 0.5, v[226:227] op_sel_hi:[1,0,1]
	v_pk_fma_f32 v[66:67], v[66:67], 0.5, v[228:229] op_sel_hi:[1,0,1]
	v_cvt_pk_bf16_f32 v180, v68, v69
	v_cvt_pk_bf16_f32 v181, v70, v71
	v_cvt_pk_bf16_f32 v182, v64, v65
	v_cvt_pk_bf16_f32 v183, v66, v67
	global_store_dwordx4 v207, v[180:183], s[18:19] offset:256
	v_pk_mul_f32 v[230:231], v[68:69], v[68:69]
	v_pk_fma_f32 v[230:231], v[70:71], v[70:71], v[230:231]
	v_pk_fma_f32 v[230:231], v[64:65], v[64:65], v[230:231]
	v_pk_fma_f32 v[230:231], v[66:67], v[66:67], v[230:231]
	v_pk_add_f32 v[220:221], v[220:221], v[230:231]
	v_add_f32_e32 v215, v220, v221
	s_waitcnt vmcnt(14)
	v_lshlrev_b32_e32 v222, 16, v184
	v_and_b32_e32 v223, 0xffff0000, v184
	v_lshlrev_b32_e32 v224, 16, v185
	v_and_b32_e32 v225, 0xffff0000, v185
	v_lshlrev_b32_e32 v226, 16, v186
	v_and_b32_e32 v227, 0xffff0000, v186
	v_lshlrev_b32_e32 v228, 16, v187
	v_and_b32_e32 v229, 0xffff0000, v187
	v_pk_fma_f32 v[60:61], v[60:61], 0.5, v[222:223] op_sel_hi:[1,0,1]
	v_pk_fma_f32 v[62:63], v[62:63], 0.5, v[224:225] op_sel_hi:[1,0,1]
	v_pk_fma_f32 v[56:57], v[56:57], 0.5, v[226:227] op_sel_hi:[1,0,1]
	v_pk_fma_f32 v[58:59], v[58:59], 0.5, v[228:229] op_sel_hi:[1,0,1]
	v_cvt_pk_bf16_f32 v184, v60, v61
	v_cvt_pk_bf16_f32 v185, v62, v63
	v_cvt_pk_bf16_f32 v186, v56, v57
	v_cvt_pk_bf16_f32 v187, v58, v59
	global_store_dwordx4 v208, v[184:187], s[18:19]
	v_pk_mul_f32 v[220:221], v[60:61], v[60:61]
	v_pk_fma_f32 v[220:221], v[62:63], v[62:63], v[220:221]
	v_pk_fma_f32 v[220:221], v[56:57], v[56:57], v[220:221]
	v_pk_fma_f32 v[220:221], v[58:59], v[58:59], v[220:221]
	v_lshlrev_b32_e32 v222, 16, v188
	v_and_b32_e32 v223, 0xffff0000, v188
	v_lshlrev_b32_e32 v224, 16, v189
	v_and_b32_e32 v225, 0xffff0000, v189
	v_lshlrev_b32_e32 v226, 16, v190
	v_and_b32_e32 v227, 0xffff0000, v190
	v_lshlrev_b32_e32 v228, 16, v191
	v_and_b32_e32 v229, 0xffff0000, v191
	v_pk_fma_f32 v[52:53], v[52:53], 0.5, v[222:223] op_sel_hi:[1,0,1]
	v_pk_fma_f32 v[54:55], v[54:55], 0.5, v[224:225] op_sel_hi:[1,0,1]
	v_pk_fma_f32 v[48:49], v[48:49], 0.5, v[226:227] op_sel_hi:[1,0,1]
	v_pk_fma_f32 v[50:51], v[50:51], 0.5, v[228:229] op_sel_hi:[1,0,1]
	v_cvt_pk_bf16_f32 v188, v52, v53
	v_cvt_pk_bf16_f32 v189, v54, v55
	v_cvt_pk_bf16_f32 v190, v48, v49
	v_cvt_pk_bf16_f32 v191, v50, v51
	global_store_dwordx4 v208, v[188:191], s[18:19] offset:256
	v_pk_mul_f32 v[230:231], v[52:53], v[52:53]
	v_pk_fma_f32 v[230:231], v[54:55], v[54:55], v[230:231]
	v_pk_fma_f32 v[230:231], v[48:49], v[48:49], v[230:231]
	v_pk_fma_f32 v[230:231], v[50:51], v[50:51], v[230:231]
	v_pk_add_f32 v[220:221], v[220:221], v[230:231]
	v_add_f32_e32 v216, v220, v221
	s_waitcnt vmcnt(14)
; __device__ __forceinline__ unsigned cvtpk(float lo, float hi) { f32x2_t v = {lo, hi}; bf16x2_t b = __builtin_convertvector(v, bf16x2_t); return __builtin_bit_cast(unsigned, b); }
; __device__ __forceinline__ float bflo(unsigned w) { return __uint_as_float(w << 16); }
; template <class Epi>
; __device__ __forceinline__ void gemm_phase(LAS unsigned char* lds, const Gemm g, const StaticOrder& S, const Epi& E, int wave_s) {
;     ...
;         if (wr == 0) PG8_BAR;
;         E(acc, cur, wr, wc, fr, fq);
;         if (!has_next) break;
; #pragma unroll
;         for (int a = 0; a < 2; ++a)
; #pragma unroll
;             for (int b = 0; b < 2; ++b)
; #pragma unroll
;                 for (int m = 0; m < 4; ++m)
; #pragma unroll
;                     for (int n = 0; n < 2; ++n) acc[a][b][m][n] = (f32x4){0.f, 0.f, 0.f, 0.f};
;         cur = nxt; cA = nA; cB = nB; ++ui;
;         if (wr == 1) PG8_BAR;
;     __device__ __forceinline__ void operator()(const f32x4 (&acc)[2][2][4][2], const Unit& u, int wr, int wc, int fr, int fq) const {
;     ...
;                 const int row = row0 + ai * HALF + m * 16; float s = 0.f;
; #pragma unroll
;                 for (int bj = 0; bj < 2; ++bj) {
;                     const size_t off = (size_t)row * DM + col0 + bj * HALF;
;                     f32x4 v0, v1;
;                     if (RM == 0) { v0 = *(const f32x4*)(xf + off); v1 = *(const f32x4*)(xf + off + 4); }
;                     else { const u32x4 w = xv[RM == 0 ? 0 : ai][RM == 0 ? 0 : m][RM == 0 ? 0 : bj]; v0 = (f32x4){bflo(w.x), bfhi(w.x), bflo(w.y), bfhi(w.y)}; v1 = (f32x4){bflo(w.z), bfhi(w.z), bflo(w.w), bfhi(w.w)}; }
;                     v0 = v0 + acc[ai][bj][m][0] * alpha; v1 = v1 + acc[ai][bj][m][1] * alpha;
;                     if (RM == 2) { *(f32x4*)(outf + off) = v0; *(f32x4*)(outf + off + 4) = v1; }
;                     else {
;                         u32x4 w; w.x = cvtpk(v0[0], v0[1]); w.y = cvtpk(v0[2], v0[3]); w.z = cvtpk(v1[0], v1[1]); w.w = cvtpk(v1[2], v1[3]);
;                         *(u32x4*)(xb + off) = w;
;                         s += (v0[0] * v0[0] + v0[1] * v0[1]) + (v0[2] * v0[2] + v0[3] * v0[3]) + (v1[0] * v1[0] + v1[1] * v1[1]) + (v1[2] * v1[2] + v1[3] * v1[3]);
;                     }
;                 }
;                 if (RM != 2) { s += __shfl_xor(s, 16); s += __shfl_xor(s, 32); if (fq == 0) ssq_out[(size_t)row * 16 + u.pn * 4 + wc] = s; }
	v_lshlrev_b32_e32 v222, 16, v120
	v_and_b32_e32 v223, 0xffff0000, v120
	v_lshlrev_b32_e32 v224, 16, v121
	v_and_b32_e32 v225, 0xffff0000, v121
	v_lshlrev_b32_e32 v226, 16, v122
	v_and_b32_e32 v227, 0xffff0000, v122
	v_lshlrev_b32_e32 v228, 16, v123
	v_and_b32_e32 v229, 0xffff0000, v123
	v_pk_fma_f32 v[44:45], v[44:45], 0.5, v[222:223] op_sel_hi:[1,0,1]
	v_pk_fma_f32 v[46:47], v[46:47], 0.5, v[224:225] op_sel_hi:[1,0,1]
	v_pk_fma_f32 v[40:41], v[40:41], 0.5, v[226:227] op_sel_hi:[1,0,1]
	v_pk_fma_f32 v[42:43], v[42:43], 0.5, v[228:229] op_sel_hi:[1,0,1]
	v_cvt_pk_bf16_f32 v120, v44, v45
	v_cvt_pk_bf16_f32 v121, v46, v47
	v_cvt_pk_bf16_f32 v122, v40, v41
	v_cvt_pk_bf16_f32 v123, v42, v43
	global_store_dwordx4 v209, v[120:123], s[18:19]
	v_pk_mul_f32 v[220:221], v[44:45], v[44:45]
	v_pk_fma_f32 v[220:221], v[46:47], v[46:47], v[220:221]
	v_pk_fma_f32 v[220:221], v[40:41], v[40:41], v[220:221]
	v_pk_fma_f32 v[220:221], v[42:43], v[42:43], v[220:221]
	v_lshlrev_b32_e32 v222, 16, v124
	v_and_b32_e32 v223, 0xffff0000, v124
	v_lshlrev_b32_e32 v224, 16, v125
	v_and_b32_e32 v225, 0xffff0000, v125
	v_lshlrev_b32_e32 v226, 16, v126
	v_and_b32_e32 v227, 0xffff0000, v126
	v_lshlrev_b32_e32 v228, 16, v127
	v_and_b32_e32 v229, 0xffff0000, v127
	v_pk_fma_f32 v[36:37], v[36:37], 0.5, v[222:223] op_sel_hi:[1,0,1]
	v_pk_fma_f32 v[38:39], v[38:39], 0.5, v[224:225] op_sel_hi:[1,0,1]
	v_pk_fma_f32 v[32:33], v[32:33], 0.5, v[226:227] op_sel_hi:[1,0,1]
	v_pk_fma_f32 v[34:35], v[34:35], 0.5, v[228:229] op_sel_hi:[1,0,1]
	v_cvt_pk_bf16_f32 v124, v36, v37
	v_cvt_pk_bf16_f32 v125, v38, v39
	v_cvt_pk_bf16_f32 v126, v32, v33
	v_cvt_pk_bf16_f32 v127, v34, v35
	global_store_dwordx4 v209, v[124:127], s[18:19] offset:256
	v_pk_mul_f32 v[230:231], v[36:37], v[36:37]
	v_pk_fma_f32 v[230:231], v[38:39], v[38:39], v[230:231]
	v_pk_fma_f32 v[230:231], v[32:33], v[32:33], v[230:231]
	v_pk_fma_f32 v[230:231], v[34:35], v[34:35], v[230:231]
	v_pk_add_f32 v[220:221], v[220:221], v[230:231]
	v_add_f32_e32 v217, v220, v221
	s_waitcnt vmcnt(14)
	v_lshlrev_b32_e32 v222, 16, v128
	v_and_b32_e32 v223, 0xffff0000, v128
	v_lshlrev_b32_e32 v224, 16, v129
	v_and_b32_e32 v225, 0xffff0000, v129
	v_lshlrev_b32_e32 v226, 16, v130
	v_and_b32_e32 v227, 0xffff0000, v130
	v_lshlrev_b32_e32 v228, 16, v131
	v_and_b32_e32 v229, 0xffff0000, v131
	v_pk_fma_f32 v[28:29], v[28:29], 0.5, v[222:223] op_sel_hi:[1,0,1]
	v_pk_fma_f32 v[30:31], v[30:31], 0.5, v[224:225] op_sel_hi:[1,0,1]
	v_pk_fma_f32 v[24:25], v[24:25], 0.5, v[226:227] op_sel_hi:[1,0,1]
	v_pk_fma_f32 v[26:27], v[26:27], 0.5, v[228:229] op_sel_hi:[1,0,1]
	v_cvt_pk_bf16_f32 v128, v28, v29
	v_cvt_pk_bf16_f32 v129, v30, v31
	v_cvt_pk_bf16_f32 v130, v24, v25
	v_cvt_pk_bf16_f32 v131, v26, v27
	global_store_dwordx4 v210, v[128:131], s[18:19]
	v_pk_mul_f32 v[220:221], v[28:29], v[28:29]
	v_pk_fma_f32 v[220:221], v[30:31], v[30:31], v[220:221]
	v_pk_fma_f32 v[220:221], v[24:25], v[24:25], v[220:221]
	v_pk_fma_f32 v[220:221], v[26:27], v[26:27], v[220:221]
	v_lshlrev_b32_e32 v222, 16, v132
	v_and_b32_e32 v223, 0xffff0000, v132
	v_lshlrev_b32_e32 v224, 16, v133
	v_and_b32_e32 v225, 0xffff0000, v133
	v_lshlrev_b32_e32 v226, 16, v134
	v_and_b32_e32 v227, 0xffff0000, v134
	v_lshlrev_b32_e32 v228, 16, v135
	v_and_b32_e32 v229, 0xffff0000, v135
	v_pk_fma_f32 v[20:21], v[20:21], 0.5, v[222:223] op_sel_hi:[1,0,1]
	v_pk_fma_f32 v[22:23], v[22:23], 0.5, v[224:225] op_sel_hi:[1,0,1]
	v_pk_fma_f32 v[16:17], v[16:17], 0.5, v[226:227] op_sel_hi:[1,0,1]
	v_pk_fma_f32 v[18:19], v[18:19], 0.5, v[228:229] op_sel_hi:[1,0,1]
	v_cvt_pk_bf16_f32 v132, v20, v21
	v_cvt_pk_bf16_f32 v133, v22, v23
	v_cvt_pk_bf16_f32 v134, v16, v17
	v_cvt_pk_bf16_f32 v135, v18, v19
	global_store_dwordx4 v210, v[132:135], s[18:19] offset:256
	v_pk_mul_f32 v[230:231], v[20:21], v[20:21]
	v_pk_fma_f32 v[230:231], v[22:23], v[22:23], v[230:231]
	v_pk_fma_f32 v[230:231], v[16:17], v[16:17], v[230:231]
	v_pk_fma_f32 v[230:231], v[18:19], v[18:19], v[230:231]
	v_pk_add_f32 v[220:221], v[220:221], v[230:231]
	v_add_f32_e32 v218, v220, v221
	s_waitcnt vmcnt(14)
	v_lshlrev_b32_e32 v222, 16, v136
	v_and_b32_e32 v223, 0xffff0000, v136
	v_lshlrev_b32_e32 v224, 16, v137
	v_and_b32_e32 v225, 0xffff0000, v137
	v_lshlrev_b32_e32 v226, 16, v138
	v_and_b32_e32 v227, 0xffff0000, v138
	v_lshlrev_b32_e32 v228, 16, v139
	v_and_b32_e32 v229, 0xffff0000, v139
	v_pk_fma_f32 v[12:13], v[12:13], 0.5, v[222:223] op_sel_hi:[1,0,1]
	v_pk_fma_f32 v[14:15], v[14:15], 0.5, v[224:225] op_sel_hi:[1,0,1]
	v_pk_fma_f32 v[8:9], v[8:9], 0.5, v[226:227] op_sel_hi:[1,0,1]
	v_pk_fma_f32 v[10:11], v[10:11], 0.5, v[228:229] op_sel_hi:[1,0,1]
	v_cvt_pk_bf16_f32 v136, v12, v13
	v_cvt_pk_bf16_f32 v137, v14, v15
	v_cvt_pk_bf16_f32 v138, v8, v9
	v_cvt_pk_bf16_f32 v139, v10, v11
	global_store_dwordx4 v211, v[136:139], s[18:19]
	v_pk_mul_f32 v[220:221], v[12:13], v[12:13]
	v_pk_fma_f32 v[220:221], v[14:15], v[14:15], v[220:221]
	v_pk_fma_f32 v[220:221], v[8:9], v[8:9], v[220:221]
	v_pk_fma_f32 v[220:221], v[10:11], v[10:11], v[220:221]
	v_lshlrev_b32_e32 v222, 16, v140
	v_and_b32_e32 v223, 0xffff0000, v140
	v_lshlrev_b32_e32 v224, 16, v141
	v_and_b32_e32 v225, 0xffff0000, v141
	v_lshlrev_b32_e32 v226, 16, v142
	v_and_b32_e32 v227, 0xffff0000, v142
	v_lshlrev_b32_e32 v228, 16, v143
	v_and_b32_e32 v229, 0xffff0000, v143
	v_pk_fma_f32 v[4:5], v[4:5], 0.5, v[222:223] op_sel_hi:[1,0,1]
	v_pk_fma_f32 v[6:7], v[6:7], 0.5, v[224:225] op_sel_hi:[1,0,1]
	v_pk_fma_f32 v[0:1], v[0:1], 0.5, v[226:227] op_sel_hi:[1,0,1]
	v_pk_fma_f32 v[2:3], v[2:3], 0.5, v[228:229] op_sel_hi:[1,0,1]
	v_cvt_pk_bf16_f32 v140, v4, v5
	v_cvt_pk_bf16_f32 v141, v6, v7
	v_cvt_pk_bf16_f32 v142, v0, v1
	v_cvt_pk_bf16_f32 v143, v2, v3
	global_store_dwordx4 v211, v[140:143], s[18:19] offset:256
	v_pk_mul_f32 v[230:231], v[4:5], v[4:5]
	v_pk_fma_f32 v[230:231], v[6:7], v[6:7], v[230:231]
	v_pk_fma_f32 v[230:231], v[0:1], v[0:1], v[230:231]
	v_pk_fma_f32 v[230:231], v[2:3], v[2:3], v[230:231]
	v_pk_add_f32 v[220:221], v[220:221], v[230:231]
	v_add_f32_e32 v219, v220, v221
	s_nop 1
	v_permlane32_swap_b32_e32 v212, v213
	v_permlane32_swap_b32_e32 v214, v215
	v_permlane32_swap_b32_e32 v216, v217
	v_permlane32_swap_b32_e32 v218, v219
	v_add_f32_e32 v212, v212, v213
	v_add_f32_e32 v214, v214, v215
	v_add_f32_e32 v216, v216, v217
	v_add_f32_e32 v218, v218, v219
	s_nop 1
	v_permlane16_swap_b32_e32 v212, v214
	v_permlane16_swap_b32_e32 v216, v218
	v_add_f32_e32 v212, v212, v214
	v_add_f32_e32 v216, v216, v218
	global_store_dword v236, v212, s[20:21]
	global_store_dword v237, v216, s[20:21]
	s_and_b64 vcc, exec, s[8:9]
	s_mov_b64 s[8:9], -1
	s_cbranch_vccnz .LBB0_1126
	s_andn2_b64 vcc, exec, s[16:17]
	s_cbranch_vccnz .LBB0_1125
	s_barrier
	s_branch .LBB0_1125
